# mLSTM output unit: the eight LDS read-modify-write rounds of the direction combine pipelined two deep with counted lgkmcnt waits
# baseline (speedup 1.0000x reference)
; #define LAS __attribute__((address_space(3)))
; __device__ __forceinline__ void mlstm_c_phase(int u_first, int G, bool skip_ctx, const bf16* Z, const float* GATES, const float* gbias, const float* gh  , const bf16* DC, const float* DN, const float* SC,
;                                               bf16* Y, LAS unsigned char* L, int tid) {
;     ...
;     if (dir == 0) {
; #pragma unroll
;         for (int et = 0; et < 2; ++et)
; #pragma unroll
;             for (int lt = 0; lt < 4; ++lt) { LAS f32x4* hp = (LAS f32x4*)(HM + (16 * lt + fr) * HMS + 16 * (2 * w4 + et) + 4 * fq); *hp = *hp + acc[et][lt]; }
;     }
.LBB0_945:
	s_or_b64 exec, exec, s[6:7]
	s_waitcnt lgkmcnt(0)
	s_barrier
	s_and_saveexec_b64 s[6:7], s[2:3]
	s_cbranch_execz .LBB0_947
	v_lshl_add_u32 v59, v145, 7, s58
	v_add3_u32 v32, v59, v32, v58
	ds_read_b128 v[74:77], v32
	ds_read_b128 v[82:85], v32 offset:8448
	s_waitcnt lgkmcnt(1)
	v_pk_add_f32 v[76:77], v[110:111], v[76:77]
	v_pk_add_f32 v[74:75], v[108:109], v[74:75]
	ds_write_b128 v32, v[74:77]
	ds_read_b128 v[74:77], v32 offset:16896
	s_waitcnt lgkmcnt(2)
	v_pk_add_f32 v[84:85], v[88:89], v[84:85]
	v_pk_add_f32 v[82:83], v[86:87], v[82:83]
	ds_write_b128 v32, v[82:85] offset:8448
	ds_read_b128 v[82:85], v32 offset:25344
	s_waitcnt lgkmcnt(2)
	v_pk_add_f32 v[68:69], v[68:69], v[76:77]
	v_pk_add_f32 v[66:67], v[66:67], v[74:75]
	ds_write_b128 v32, v[66:69] offset:16896
	ds_read_b128 v[74:77], v32 offset:64
	s_waitcnt lgkmcnt(2)
	v_pk_add_f32 v[84:85], v[72:73], v[84:85]
	v_pk_add_f32 v[82:83], v[70:71], v[82:83]
	ds_write_b128 v32, v[82:85] offset:25344
	ds_read_b128 v[82:85], v32 offset:8512
	s_waitcnt lgkmcnt(2)
	v_pk_add_f32 v[76:77], v[104:105], v[76:77]
	v_pk_add_f32 v[74:75], v[102:103], v[74:75]
	ds_write_b128 v32, v[74:77] offset:64
	ds_read_b128 v[74:77], v32 offset:16960
	s_waitcnt lgkmcnt(2)
	v_pk_add_f32 v[84:85], v[80:81], v[84:85]
	v_pk_add_f32 v[82:83], v[78:79], v[82:83]
	ds_write_b128 v32, v[82:85] offset:8512
	ds_read_b128 v[82:85], v32 offset:25408
	s_waitcnt lgkmcnt(2)
	v_pk_add_f32 v[62:63], v[62:63], v[76:77]
	v_pk_add_f32 v[60:61], v[60:61], v[74:75]
	ds_write_b128 v32, v[60:63] offset:16960
	s_waitcnt lgkmcnt(1)
	v_pk_add_f32 v[56:57], v[56:57], v[84:85]
	v_pk_add_f32 v[54:55], v[54:55], v[82:83]
	ds_write_b128 v32, v[54:57] offset:25408
